# LN1 top-4 rank loop: the four logit LDS reads per iteration issued together with counted lgkmcnt waits
# baseline (speedup 1.0000x reference)
; __device__ __forceinline__ void lds_fence() { asm volatile("s_waitcnt lgkmcnt(0)" ::: "memory"); }
; __device__ __forceinline__ void ln1_router_phase(const Args& a, int l, LAS unsigned char* lds, const int tid, const int rpt) {
;     ...
;         { const int t = tid >> 5, e = tid & 31; const float v = LG[tid]; int rank = 0;
; #pragma unroll 8
;           for (int j = 0; j < 32; ++j) { const float o = LG[t * 32 + j]; rank += (o > v || (o == v && j < e)) ? 1 : 0; }
;           const bool sel = rank < 4;
;           if (sel) TV[t * 4 + rank] = v;
;           lds_fence();
;           if (sel) { const float m = TV[t * 4], den = ((__expf(TV[t * 4] - m) + __expf(TV[t * 4 + 1] - m)) + __expf(TV[t * 4 + 2] - m)) + __expf(TV[t * 4 + 3] - m);
;               const float gate = __expf(v - m) * (1.0f / den); const int tok = tok0 + t, k = rank;
;               if (rpt == 0) { const int s = tok * 4 + k; slot_e[s] = e; slot_g[s] = gate;
;                   if (iloc < MAXLOC) { const int lpos = atomicAdd((int*)&LCNT[e], 1); LSLOT[iloc * 64 + t * 4 + k] = (e << 16) | lpos; }
;                   else { const int pos = atomicAdd(cnt + e, 1); slot_pos[s] = pos; } } }
;           lds_fence(); }
.LBB0_126:
	v_add_u32_e32 v70, s22, v150
	v_add_u32_e32 v66, 0x14100, v70
	ds_read_b128 v[66:69], v66
	v_add_u32_e32 v176, 0x14110, v70
	ds_read_b128 v[176:179], v176
	v_add_u32_e32 v180, 0x14120, v70
	ds_read_b128 v[180:183], v180
	v_add_u32_e32 v184, 0x14130, v70
	ds_read_b128 v[184:187], v184
	v_cmp_lt_u32_e64 s[44:45], s23, v44
	v_cmp_lt_u32_e64 s[46:47], s12, v39
	s_add_i32 s22, s22, 64
	s_waitcnt lgkmcnt(3)
	v_cmp_eq_f32_e64 s[38:39], v66, v32
	v_cmp_eq_f32_e64 s[40:41], v67, v45
	v_cmp_gt_f32_e32 vcc, v67, v45
	v_cmp_gt_f32_e64 s[0:1], v66, v32
	s_and_b64 s[40:41], s[40:41], s[46:47]
	s_and_b64 s[38:39], s[38:39], s[44:45]
	s_or_b64 s[0:1], s[0:1], s[38:39]
	s_or_b64 s[38:39], vcc, s[40:41]
	s_add_i32 s46, s23, 2
	s_add_i32 s44, s12, 2
	v_cndmask_b32_e64 v66, 0, 1, s[38:39]
	v_cmp_eq_f32_e64 s[38:39], v69, v45
	v_cmp_eq_f32_e64 s[40:41], v68, v32
	v_cmp_lt_u32_e64 s[44:45], s44, v39
	v_cmp_lt_u32_e64 s[46:47], s46, v44
	v_cndmask_b32_e64 v67, 0, 1, s[0:1]
	v_cmp_gt_f32_e32 vcc, v68, v32
	v_cmp_gt_f32_e64 s[0:1], v69, v45
	s_and_b64 s[40:41], s[40:41], s[46:47]
	s_and_b64 s[38:39], s[38:39], s[44:45]
	s_or_b64 s[0:1], s[0:1], s[38:39]
	s_or_b64 vcc, vcc, s[40:41]
	v_addc_co_u32_e32 v68, vcc, v65, v67, vcc
	v_addc_co_u32_e64 v69, vcc, v64, v66, s[0:1]
	s_add_i32 s46, s23, 4
	s_add_i32 s44, s12, 4
	v_cmp_lt_u32_e64 s[44:45], s44, v39
	v_cmp_lt_u32_e64 s[46:47], s46, v44
	s_waitcnt lgkmcnt(2)
	v_cmp_eq_f32_e64 s[38:39], v177, v45
	v_cmp_eq_f32_e64 s[40:41], v176, v32
	v_cmp_gt_f32_e32 vcc, v176, v32
	v_cmp_gt_f32_e64 s[0:1], v177, v45
	s_and_b64 s[40:41], s[40:41], s[46:47]
	s_and_b64 s[38:39], s[38:39], s[44:45]
	s_or_b64 s[0:1], s[0:1], s[38:39]
	s_or_b64 s[38:39], vcc, s[40:41]
	s_add_i32 s46, s12, 6
	s_add_i32 s44, s23, 6
	v_cndmask_b32_e64 v64, 0, 1, s[38:39]
	v_cmp_eq_f32_e64 s[38:39], v178, v32
	v_cmp_eq_f32_e64 s[40:41], v179, v45
	v_cmp_lt_u32_e64 s[44:45], s44, v44
	v_cmp_lt_u32_e64 s[46:47], s46, v39
	v_cndmask_b32_e64 v65, 0, 1, s[0:1]
	v_cmp_gt_f32_e32 vcc, v179, v45
	v_cmp_gt_f32_e64 s[0:1], v178, v32
	s_and_b64 s[40:41], s[40:41], s[46:47]
	s_and_b64 s[38:39], s[38:39], s[44:45]
	s_or_b64 s[0:1], s[0:1], s[38:39]
	s_or_b64 vcc, vcc, s[40:41]
	v_addc_co_u32_e32 v69, vcc, v69, v65, vcc
	v_addc_co_u32_e64 v68, vcc, v68, v64, s[0:1]
	s_add_i32 s46, s12, 8
	s_add_i32 s44, s23, 8
	v_cmp_lt_u32_e64 s[44:45], s44, v44
	v_cmp_lt_u32_e64 s[46:47], s46, v39
	s_waitcnt lgkmcnt(1)
	v_cmp_eq_f32_e64 s[38:39], v180, v32
	v_cmp_eq_f32_e64 s[40:41], v181, v45
	v_cmp_gt_f32_e32 vcc, v181, v45
	v_cmp_gt_f32_e64 s[0:1], v180, v32
	s_and_b64 s[40:41], s[40:41], s[46:47]
	s_and_b64 s[38:39], s[38:39], s[44:45]
	s_or_b64 s[0:1], s[0:1], s[38:39]
	s_or_b64 s[38:39], vcc, s[40:41]
	s_add_i32 s46, s23, 10
	s_add_i32 s44, s12, 10
	v_cndmask_b32_e64 v64, 0, 1, s[38:39]
	v_cmp_eq_f32_e64 s[38:39], v183, v45
	v_cmp_eq_f32_e64 s[40:41], v182, v32
	v_cmp_lt_u32_e64 s[44:45], s44, v39
	v_cmp_lt_u32_e64 s[46:47], s46, v44
	v_cndmask_b32_e64 v65, 0, 1, s[0:1]
	v_cmp_gt_f32_e32 vcc, v182, v32
	v_cmp_gt_f32_e64 s[0:1], v183, v45
	s_and_b64 s[40:41], s[40:41], s[46:47]
	s_and_b64 s[38:39], s[38:39], s[44:45]
	s_or_b64 s[0:1], s[0:1], s[38:39]
	s_or_b64 vcc, vcc, s[40:41]
	v_addc_co_u32_e32 v68, vcc, v68, v65, vcc
	v_addc_co_u32_e64 v69, vcc, v69, v64, s[0:1]
	s_add_i32 s46, s23, 12
	s_add_i32 s44, s12, 12
	v_cmp_lt_u32_e64 s[44:45], s44, v39
	v_cmp_lt_u32_e64 s[46:47], s46, v44
	s_waitcnt lgkmcnt(0)
	v_cmp_eq_f32_e64 s[38:39], v185, v45
	v_cmp_eq_f32_e64 s[40:41], v184, v32
	v_cmp_gt_f32_e32 vcc, v184, v32
	v_cmp_gt_f32_e64 s[0:1], v185, v45
	s_and_b64 s[40:41], s[40:41], s[46:47]
	s_and_b64 s[38:39], s[38:39], s[44:45]
	s_or_b64 s[0:1], s[0:1], s[38:39]
	s_or_b64 s[38:39], vcc, s[40:41]
	s_add_i32 s46, s12, 14
	s_add_i32 s44, s23, 14
	v_cndmask_b32_e64 v65, 0, 1, s[38:39]
	v_cmp_eq_f32_e64 s[38:39], v186, v32
	v_cmp_eq_f32_e64 s[40:41], v187, v45
	v_cmp_lt_u32_e64 s[44:45], s44, v44
	v_cmp_lt_u32_e64 s[46:47], s46, v39
	v_cndmask_b32_e64 v64, 0, 1, s[0:1]
	v_cmp_gt_f32_e32 vcc, v187, v45
	v_cmp_gt_f32_e64 s[0:1], v186, v32
	s_and_b64 s[40:41], s[40:41], s[46:47]
	s_and_b64 s[38:39], s[38:39], s[44:45]
	s_or_b64 s[0:1], s[0:1], s[38:39]
	s_or_b64 vcc, vcc, s[40:41]
	s_add_i32 s23, s23, 16
	s_add_i32 s12, s12, 16
	v_addc_co_u32_e32 v64, vcc, v69, v64, vcc
	v_addc_co_u32_e64 v65, vcc, v68, v65, s[0:1]
	s_cmpk_lg_i32 s22, 0x80
	s_cbranch_scc1 .LBB0_126
	v_add_u32_e32 v45, v65, v64
	v_cmp_lt_u32_e32 vcc, 3, v45
	v_cmp_gt_u32_e64 s[0:1], 4, v45
	s_and_saveexec_b64 s[22:23], s[0:1]
	v_lshl_add_u32 v64, v45, 2, v144
	ds_write_b32 v64, v32
	s_or_b64 exec, exec, s[22:23]
	s_waitcnt lgkmcnt(0)
	s_nor_b64 s[22:23], s[16:17], vcc
	s_and_saveexec_b64 s[0:1], s[22:23]
	s_cbranch_execz .LBB0_122
	ds_read_b128 v[64:67], v144
	v_add_u32_e32 v68, s51, v143
	s_cmp_gt_u32 s26, 15
	s_waitcnt lgkmcnt(0)
	v_sub_f32_e32 v32, v32, v64
	v_sub_f32_e32 v67, v67, v64
	v_sub_f32_e32 v66, v66, v64
	v_sub_f32_e32 v65, v65, v64
	v_sub_f32_e32 v64, v64, v64
	v_mul_f32_e32 v65, 0x3fb8aa3b, v65
	v_mul_f32_e32 v64, 0x3fb8aa3b, v64
	v_mul_f32_e32 v66, 0x3fb8aa3b, v66
	v_exp_f32_e32 v65, v65
	v_exp_f32_e32 v64, v64
	v_mul_f32_e32 v67, 0x3fb8aa3b, v67
	v_exp_f32_e32 v66, v66
	v_exp_f32_e32 v67, v67
	v_add_f32_e32 v64, v64, v65
	v_mul_f32_e32 v32, 0x3fb8aa3b, v32
	v_add_f32_e32 v64, v66, v64
	v_add_f32_e32 v64, v67, v64
	v_div_scale_f32 v65, s[22:23], v64, v64, 1.0
	v_rcp_f32_e32 v66, v65
	v_exp_f32_e32 v32, v32
	v_readlane_b32 s22, v251, 41
	v_readlane_b32 s23, v251, 42
	v_fma_f32 v67, -v65, v66, 1.0
	v_fmac_f32_e32 v66, v67, v66
	v_div_scale_f32 v67, vcc, 1.0, v64, 1.0
	v_mul_f32_e32 v69, v67, v66
	v_fma_f32 v70, -v65, v69, v67
	v_fmac_f32_e32 v69, v70, v66
	v_fma_f32 v65, -v65, v69, v67
	v_div_fmas_f32 v65, v65, v66, v69
	v_div_fixup_f32 v64, v65, v64, 1.0
	v_mul_f32_e32 v32, v32, v64
	v_lshl_or_b32 v64, v68, 2, v45
	v_ashrrev_i32_e32 v65, 31, v64
	v_lshlrev_b64 v[66:67], 2, v[64:65]
	v_lshl_add_u64 v[68:69], s[22:23], 0, v[66:67]
	v_readlane_b32 s22, v251, 43
	v_readlane_b32 s23, v251, 44
	global_store_dword v[68:69], v44, off
	s_nop 0
	v_lshl_add_u64 v[66:67], s[22:23], 0, v[66:67]
	s_mov_b64 s[22:23], -1
	global_store_dword v[66:67], v32, off
	s_cbranch_scc0 .LBB0_132
	v_mov_b32_e32 v32, 1
	global_atomic_add v32, v[56:57], v32, off sc0
	v_readlane_b32 s22, v254, 42
	v_readlane_b32 s23, v254, 43
	s_nop 1
	v_lshl_add_u64 v[64:65], v[64:65], 2, s[22:23]
	s_mov_b64 s[22:23], 0
	s_waitcnt vmcnt(0)
	global_store_dword v[64:65], v32, off
